# best + LT (s_setprio 1 ahead of the load segment's waits; m0 write reordered ahead of the address VALU so the s_nop before each LDS-DMA load goes)
# baseline (speedup 1.0000x reference)
.LBB0_139:
	s_add_i32 s49, 0, 0x10000
	s_add_i32 s52, 0, 0x14000
	v_add_u32_e32 v156, s49, v145
	v_add_u32_e32 v172, s52, v145
	ds_read_b128 v[140:143], v156
	ds_read_b128 v[148:151], v156 offset:1024
	ds_read_b128 v[152:155], v156 offset:2048
	ds_read_b128 v[156:159], v156 offset:3072
	ds_read_b128 v[160:163], v172
	ds_read_b128 v[164:167], v172 offset:1024
	ds_read_b128 v[168:171], v172 offset:2048
	ds_read_b128 v[190:193], v172 offset:3072
	v_lshl_add_u64 v[172:173], s[18:19], 0, v[136:137]
	s_add_i32 m0, s31, 0xc000
	ds_read_b128 v[194:197], v147
	ds_read_b128 v[198:201], v147 offset:1024
	ds_read_b128 v[202:205], v147 offset:2048
	ds_read_b128 v[206:209], v147 offset:3072
	ds_read_b128 v[228:231], v147 offset:4096
	ds_read_b128 v[232:235], v147 offset:5120
	ds_read_b128 v[236:239], v147 offset:6144
	ds_read_b128 v[240:243], v147 offset:7168
	global_load_lds_dwordx4 v[172:173], off
	s_add_i32 m0, s31, 0xe000
	v_lshl_add_u64 v[172:173], s[18:19], 0, v[138:139]
	global_load_lds_dwordx4 v[172:173], off
	s_cmp_eq_u32 s48, -2
	s_cbranch_scc1 .Lz0_0_0
	s_setprio 1
	s_waitcnt vmcnt(8)
	s_waitcnt lgkmcnt(0)
	s_barrier
	v_mfma_f32_16x16x32_bf16 v[126:129], v[140:143], v[194:197], v[126:129]
	v_mfma_f32_16x16x32_bf16 v[126:129], v[148:151], v[198:201], v[126:129]
	v_mfma_f32_16x16x32_bf16 v[118:121], v[148:151], v[206:209], v[118:121]
	v_mfma_f32_16x16x32_bf16 v[118:121], v[140:143], v[202:205], v[118:121]
	v_mfma_f32_16x16x32_bf16 v[102:105], v[140:143], v[228:231], v[102:105]
	v_mfma_f32_16x16x32_bf16 v[102:105], v[148:151], v[232:235], v[102:105]
	v_mfma_f32_16x16x32_bf16 v[86:89], v[148:151], v[240:243], v[86:89]
	v_mfma_f32_16x16x32_bf16 v[86:89], v[140:143], v[236:239], v[86:89]
	v_mfma_f32_16x16x32_bf16 v[78:81], v[152:155], v[236:239], v[78:81]
	v_mfma_f32_16x16x32_bf16 v[78:81], v[156:159], v[240:243], v[78:81]
	v_mfma_f32_16x16x32_bf16 v[94:97], v[156:159], v[232:235], v[94:97]
	v_mfma_f32_16x16x32_bf16 v[94:97], v[152:155], v[228:231], v[94:97]
	v_mfma_f32_16x16x32_bf16 v[110:113], v[152:155], v[202:205], v[110:113]
	v_mfma_f32_16x16x32_bf16 v[110:113], v[156:159], v[206:209], v[110:113]
	v_mfma_f32_16x16x32_bf16 v[122:125], v[156:159], v[198:201], v[122:125]
	v_mfma_f32_16x16x32_bf16 v[122:125], v[152:155], v[194:197], v[122:125]
	v_mfma_f32_16x16x32_bf16 v[114:117], v[160:163], v[194:197], v[114:117]
	v_mfma_f32_16x16x32_bf16 v[114:117], v[164:167], v[198:201], v[114:117]
	v_mfma_f32_16x16x32_bf16 v[98:101], v[164:167], v[206:209], v[98:101]
	v_mfma_f32_16x16x32_bf16 v[98:101], v[160:163], v[202:205], v[98:101]
	v_mfma_f32_16x16x32_bf16 v[82:85], v[160:163], v[228:231], v[82:85]
	v_mfma_f32_16x16x32_bf16 v[82:85], v[164:167], v[232:235], v[82:85]
	v_mfma_f32_16x16x32_bf16 v[70:73], v[164:167], v[240:243], v[70:73]
	v_mfma_f32_16x16x32_bf16 v[70:73], v[160:163], v[236:239], v[70:73]
	v_mfma_f32_16x16x32_bf16 v[66:69], v[168:171], v[236:239], v[66:69]
	v_mfma_f32_16x16x32_bf16 v[66:69], v[190:193], v[240:243], v[66:69]
	v_mfma_f32_16x16x32_bf16 v[74:77], v[190:193], v[232:235], v[74:77]
	v_mfma_f32_16x16x32_bf16 v[74:77], v[168:171], v[228:231], v[74:77]
	v_mfma_f32_16x16x32_bf16 v[90:93], v[168:171], v[202:205], v[90:93]
	v_mfma_f32_16x16x32_bf16 v[90:93], v[190:193], v[206:209], v[90:93]
	v_mfma_f32_16x16x32_bf16 v[106:109], v[190:193], v[198:201], v[106:109]
	v_mfma_f32_16x16x32_bf16 v[106:109], v[168:171], v[194:197], v[106:109]
	s_barrier
	s_setprio 0
.Lz0_0_0_ret:
	s_add_i32 s49, s49, s26
	s_mov_b32 m0, s49
	v_lshl_add_u64 v[172:173], s[22:23], 0, v[0:1]
	global_load_lds_dwordx4 v[172:173], off
	ds_read_b128 v[194:197], v147 offset:16384
	ds_read_b128 v[198:201], v147 offset:17408
	s_add_i32 m0, s49, 0x2000
	s_add_u32 s50, s22, 0x100000
	v_lshl_add_u64 v[178:179], s[22:23], 0, v[130:131]
	s_addc_u32 s51, s23, 0
	s_add_i32 s49, s52, s26
	global_load_lds_dwordx4 v[178:179], off
	ds_read_b128 v[202:205], v147 offset:18432
	ds_read_b128 v[206:209], v147 offset:19456
	v_lshl_add_u64 v[180:181], s[50:51], 0, v[0:1]
	s_mov_b32 m0, s49
	v_lshl_add_u64 v[210:211], s[24:25], 0, v[132:133]
	global_load_lds_dwordx4 v[180:181], off
	ds_read_b128 v[228:231], v147 offset:20480
	ds_read_b128 v[232:235], v147 offset:21504
	s_add_i32 m0, s49, 0x2000
	v_lshl_add_u64 v[180:181], s[50:51], 0, v[130:131]
	global_load_lds_dwordx4 v[180:181], off
	ds_read_b128 v[236:239], v147 offset:22528
	ds_read_b128 v[240:243], v147 offset:23552
	s_mov_b32 m0, s31
	v_lshl_add_u64 v[180:181], s[24:25], 0, v[134:135]
	global_load_lds_dwordx4 v[180:181], off
	s_mov_b32 m0, s36
	s_nop 0
	global_load_lds_dwordx4 v[210:211], off
	s_cmp_eq_u32 s48, -2
	s_cbranch_scc1 .Lz0_0_1
	s_setprio 1
	s_waitcnt vmcnt(8)
	s_waitcnt lgkmcnt(0)
	s_barrier
	v_mfma_f32_16x16x32_bf16 v[62:65], v[140:143], v[194:197], v[62:65]
	v_mfma_f32_16x16x32_bf16 v[62:65], v[148:151], v[198:201], v[62:65]
	v_mfma_f32_16x16x32_bf16 v[54:57], v[148:151], v[206:209], v[54:57]
	v_mfma_f32_16x16x32_bf16 v[54:57], v[140:143], v[202:205], v[54:57]
	v_mfma_f32_16x16x32_bf16 v[38:41], v[140:143], v[228:231], v[38:41]
	v_mfma_f32_16x16x32_bf16 v[38:41], v[148:151], v[232:235], v[38:41]
	v_mfma_f32_16x16x32_bf16 v[22:25], v[148:151], v[240:243], v[22:25]
	v_mfma_f32_16x16x32_bf16 v[22:25], v[140:143], v[236:239], v[22:25]
	v_mfma_f32_16x16x32_bf16 v[14:17], v[152:155], v[236:239], v[14:17]
	v_mfma_f32_16x16x32_bf16 v[14:17], v[156:159], v[240:243], v[14:17]
	v_mfma_f32_16x16x32_bf16 v[30:33], v[156:159], v[232:235], v[30:33]
	v_mfma_f32_16x16x32_bf16 v[30:33], v[152:155], v[228:231], v[30:33]
	v_mfma_f32_16x16x32_bf16 v[46:49], v[152:155], v[202:205], v[46:49]
	v_mfma_f32_16x16x32_bf16 v[46:49], v[156:159], v[206:209], v[46:49]
	v_mfma_f32_16x16x32_bf16 v[58:61], v[156:159], v[198:201], v[58:61]
	v_mfma_f32_16x16x32_bf16 v[58:61], v[152:155], v[194:197], v[58:61]
	v_mfma_f32_16x16x32_bf16 v[50:53], v[160:163], v[194:197], v[50:53]
	v_mfma_f32_16x16x32_bf16 v[50:53], v[164:167], v[198:201], v[50:53]
	v_mfma_f32_16x16x32_bf16 v[34:37], v[164:167], v[206:209], v[34:37]
	v_mfma_f32_16x16x32_bf16 v[34:37], v[160:163], v[202:205], v[34:37]
	v_mfma_f32_16x16x32_bf16 v[18:21], v[160:163], v[228:231], v[18:21]
	v_mfma_f32_16x16x32_bf16 v[18:21], v[164:167], v[232:235], v[18:21]
	v_mfma_f32_16x16x32_bf16 v[6:9], v[164:167], v[240:243], v[6:9]
	v_mfma_f32_16x16x32_bf16 v[6:9], v[160:163], v[236:239], v[6:9]
	v_mfma_f32_16x16x32_bf16 v[2:5], v[168:171], v[236:239], v[2:5]
	v_mfma_f32_16x16x32_bf16 v[2:5], v[190:193], v[240:243], v[2:5]
	v_mfma_f32_16x16x32_bf16 v[10:13], v[190:193], v[232:235], v[10:13]
	v_mfma_f32_16x16x32_bf16 v[10:13], v[168:171], v[228:231], v[10:13]
	v_mfma_f32_16x16x32_bf16 v[26:29], v[168:171], v[202:205], v[26:29]
	v_mfma_f32_16x16x32_bf16 v[26:29], v[190:193], v[206:209], v[26:29]
	v_mfma_f32_16x16x32_bf16 v[42:45], v[190:193], v[198:201], v[42:45]
	v_mfma_f32_16x16x32_bf16 v[42:45], v[168:171], v[194:197], v[42:45]
	s_barrier
	s_setprio 0
.Lz0_0_1_ret:
	s_add_i32 s49, 0, 0x18000
	s_add_i32 s50, 0, 0x1c000
	v_add_u32_e32 v156, s49, v145
	v_add_u32_e32 v175, s50, v145
	ds_read_b128 v[140:143], v156
	ds_read_b128 v[148:151], v156 offset:1024
	ds_read_b128 v[152:155], v156 offset:2048
	ds_read_b128 v[156:159], v156 offset:3072
	ds_read_b128 v[160:163], v175
	ds_read_b128 v[164:167], v175 offset:1024
	ds_read_b128 v[168:171], v175 offset:2048
	ds_read_b128 v[190:193], v175 offset:3072
	s_add_u32 s24, s24, 0x100000
	s_addc_u32 s25, s25, 0
	s_mov_b32 m0, s37
	v_lshl_add_u64 v[244:245], s[24:25], 0, v[134:135]
	ds_read_b128 v[194:197], v147 offset:32768
	ds_read_b128 v[198:201], v147 offset:33792
	ds_read_b128 v[202:205], v147 offset:34816
	ds_read_b128 v[206:209], v147 offset:35840
	ds_read_b128 v[228:231], v147 offset:36864
	ds_read_b128 v[232:235], v147 offset:37888
	ds_read_b128 v[236:239], v147 offset:38912
	ds_read_b128 v[240:243], v147 offset:39936
	global_load_lds_dwordx4 v[244:245], off
	s_mov_b32 m0, s38
	v_lshl_add_u64 v[244:245], s[24:25], 0, v[132:133]
	global_load_lds_dwordx4 v[244:245], off
	s_setprio 1
	s_waitcnt vmcnt(8)
	s_waitcnt lgkmcnt(0)
	s_barrier
	v_mfma_f32_16x16x32_bf16 v[126:129], v[140:143], v[194:197], v[126:129]
	v_mfma_f32_16x16x32_bf16 v[126:129], v[148:151], v[198:201], v[126:129]
	v_mfma_f32_16x16x32_bf16 v[118:121], v[148:151], v[206:209], v[118:121]
	v_mfma_f32_16x16x32_bf16 v[118:121], v[140:143], v[202:205], v[118:121]
	v_mfma_f32_16x16x32_bf16 v[102:105], v[140:143], v[228:231], v[102:105]
	v_mfma_f32_16x16x32_bf16 v[102:105], v[148:151], v[232:235], v[102:105]
	v_mfma_f32_16x16x32_bf16 v[86:89], v[148:151], v[240:243], v[86:89]
	v_mfma_f32_16x16x32_bf16 v[86:89], v[140:143], v[236:239], v[86:89]
	v_mfma_f32_16x16x32_bf16 v[78:81], v[152:155], v[236:239], v[78:81]
	v_mfma_f32_16x16x32_bf16 v[78:81], v[156:159], v[240:243], v[78:81]
	v_mfma_f32_16x16x32_bf16 v[94:97], v[156:159], v[232:235], v[94:97]
	v_mfma_f32_16x16x32_bf16 v[94:97], v[152:155], v[228:231], v[94:97]
	v_mfma_f32_16x16x32_bf16 v[110:113], v[152:155], v[202:205], v[110:113]
	v_mfma_f32_16x16x32_bf16 v[110:113], v[156:159], v[206:209], v[110:113]
	v_mfma_f32_16x16x32_bf16 v[122:125], v[156:159], v[198:201], v[122:125]
	v_mfma_f32_16x16x32_bf16 v[122:125], v[152:155], v[194:197], v[122:125]
	v_mfma_f32_16x16x32_bf16 v[114:117], v[160:163], v[194:197], v[114:117]
	v_mfma_f32_16x16x32_bf16 v[114:117], v[164:167], v[198:201], v[114:117]
	v_mfma_f32_16x16x32_bf16 v[98:101], v[164:167], v[206:209], v[98:101]
	v_mfma_f32_16x16x32_bf16 v[98:101], v[160:163], v[202:205], v[98:101]
	v_mfma_f32_16x16x32_bf16 v[82:85], v[160:163], v[228:231], v[82:85]
	v_mfma_f32_16x16x32_bf16 v[82:85], v[164:167], v[232:235], v[82:85]
	v_mfma_f32_16x16x32_bf16 v[70:73], v[164:167], v[240:243], v[70:73]
	v_mfma_f32_16x16x32_bf16 v[70:73], v[160:163], v[236:239], v[70:73]
	v_mfma_f32_16x16x32_bf16 v[66:69], v[168:171], v[236:239], v[66:69]
	v_mfma_f32_16x16x32_bf16 v[66:69], v[190:193], v[240:243], v[66:69]
	v_mfma_f32_16x16x32_bf16 v[74:77], v[190:193], v[232:235], v[74:77]
	v_mfma_f32_16x16x32_bf16 v[74:77], v[168:171], v[228:231], v[74:77]
	v_mfma_f32_16x16x32_bf16 v[90:93], v[168:171], v[202:205], v[90:93]
	v_mfma_f32_16x16x32_bf16 v[90:93], v[190:193], v[206:209], v[90:93]
	v_mfma_f32_16x16x32_bf16 v[106:109], v[190:193], v[198:201], v[106:109]
	v_mfma_f32_16x16x32_bf16 v[106:109], v[168:171], v[194:197], v[106:109]
	s_barrier
	s_setprio 0
	s_add_i32 s24, s49, s26
	s_mov_b32 m0, s24
	v_lshl_add_u64 v[172:173], v[172:173], 0, s[34:35]
	global_load_lds_dwordx4 v[172:173], off
	ds_read_b128 v[194:197], v147 offset:49152
	ds_read_b128 v[198:201], v147 offset:50176
	s_add_i32 m0, s24, 0x2000
	s_add_u32 s22, s22, 0x100080
	v_lshl_add_u64 v[172:173], v[178:179], 0, s[34:35]
	s_addc_u32 s23, s23, 0
	s_add_i32 s24, s50, s26
	global_load_lds_dwordx4 v[172:173], off
	ds_read_b128 v[202:205], v147 offset:51200
	ds_read_b128 v[206:209], v147 offset:52224
	s_mov_b32 m0, s24
	v_lshl_add_u64 v[172:173], s[22:23], 0, v[0:1]
	global_load_lds_dwordx4 v[172:173], off
	ds_read_b128 v[228:231], v147 offset:53248
	ds_read_b128 v[232:235], v147 offset:54272
	s_add_i32 m0, s24, 0x2000
	v_lshl_add_u64 v[172:173], s[22:23], 0, v[130:131]
	global_load_lds_dwordx4 v[172:173], off
	ds_read_b128 v[236:239], v147 offset:55296
	ds_read_b128 v[240:243], v147 offset:56320
	s_mov_b32 m0, s39
	v_lshl_add_u64 v[172:173], v[180:181], 0, s[34:35]
	global_load_lds_dwordx4 v[172:173], off
	s_add_i32 s48, s48, 2
	s_add_u32 s18, s18, 0x100
	s_addc_u32 s19, s19, 0
	s_add_u32 s46, s46, 0x100
	s_addc_u32 s47, s47, 0
	s_add_u32 s22, s18, 0xfff00080
	s_addc_u32 s23, s19, -1
	s_cmp_eq_u32 s48, 60
	s_cselect_b32 s25, s9, s23
	s_cselect_b32 s24, s44, s22
	s_cselect_b32 s23, s7, s47
	s_cselect_b32 s22, s45, s46
	s_mov_b32 m0, s40
	v_lshl_add_u64 v[172:173], v[210:211], 0, s[34:35]
	global_load_lds_dwordx4 v[172:173], off
	s_setprio 1
	s_waitcnt vmcnt(8)
	s_waitcnt lgkmcnt(0)
	s_barrier
	v_mfma_f32_16x16x32_bf16 v[62:65], v[140:143], v[194:197], v[62:65]
	v_mfma_f32_16x16x32_bf16 v[62:65], v[148:151], v[198:201], v[62:65]
	v_mfma_f32_16x16x32_bf16 v[54:57], v[148:151], v[206:209], v[54:57]
	v_mfma_f32_16x16x32_bf16 v[54:57], v[140:143], v[202:205], v[54:57]
	v_mfma_f32_16x16x32_bf16 v[38:41], v[140:143], v[228:231], v[38:41]
	v_mfma_f32_16x16x32_bf16 v[38:41], v[148:151], v[232:235], v[38:41]
	v_mfma_f32_16x16x32_bf16 v[22:25], v[148:151], v[240:243], v[22:25]
	v_mfma_f32_16x16x32_bf16 v[22:25], v[140:143], v[236:239], v[22:25]
	v_mfma_f32_16x16x32_bf16 v[14:17], v[152:155], v[236:239], v[14:17]
	v_mfma_f32_16x16x32_bf16 v[14:17], v[156:159], v[240:243], v[14:17]
	v_mfma_f32_16x16x32_bf16 v[30:33], v[156:159], v[232:235], v[30:33]
	v_mfma_f32_16x16x32_bf16 v[30:33], v[152:155], v[228:231], v[30:33]
	v_mfma_f32_16x16x32_bf16 v[46:49], v[152:155], v[202:205], v[46:49]
	v_mfma_f32_16x16x32_bf16 v[46:49], v[156:159], v[206:209], v[46:49]
	v_mfma_f32_16x16x32_bf16 v[58:61], v[156:159], v[198:201], v[58:61]
	v_mfma_f32_16x16x32_bf16 v[58:61], v[152:155], v[194:197], v[58:61]
	v_mfma_f32_16x16x32_bf16 v[50:53], v[160:163], v[194:197], v[50:53]
	v_mfma_f32_16x16x32_bf16 v[50:53], v[164:167], v[198:201], v[50:53]
	v_mfma_f32_16x16x32_bf16 v[34:37], v[164:167], v[206:209], v[34:37]
	v_mfma_f32_16x16x32_bf16 v[34:37], v[160:163], v[202:205], v[34:37]
	v_mfma_f32_16x16x32_bf16 v[18:21], v[160:163], v[228:231], v[18:21]
	v_mfma_f32_16x16x32_bf16 v[18:21], v[164:167], v[232:235], v[18:21]
	v_mfma_f32_16x16x32_bf16 v[6:9], v[164:167], v[240:243], v[6:9]
	v_mfma_f32_16x16x32_bf16 v[6:9], v[160:163], v[236:239], v[6:9]
	v_mfma_f32_16x16x32_bf16 v[2:5], v[168:171], v[236:239], v[2:5]
	v_mfma_f32_16x16x32_bf16 v[2:5], v[190:193], v[240:243], v[2:5]
	v_mfma_f32_16x16x32_bf16 v[10:13], v[190:193], v[232:235], v[10:13]
	v_mfma_f32_16x16x32_bf16 v[10:13], v[168:171], v[228:231], v[10:13]
	v_mfma_f32_16x16x32_bf16 v[26:29], v[168:171], v[202:205], v[26:29]
	v_mfma_f32_16x16x32_bf16 v[26:29], v[190:193], v[206:209], v[26:29]
	v_mfma_f32_16x16x32_bf16 v[42:45], v[190:193], v[198:201], v[42:45]
	v_mfma_f32_16x16x32_bf16 v[42:45], v[168:171], v[194:197], v[42:45]
	s_barrier
	s_setprio 0
	s_cmp_gt_u32 s48, 61
	s_cbranch_scc0 .LBB0_139
	s_and_b64 vcc, exec, s[4:5]
	s_cbranch_vccz .LBB0_142
	s_barrier

.LBB0_575:
	s_add_i32 s53, 0, 0x10000
	v_add_u32_e32 v140, s53, v143
	s_add_i32 s56, 0, 0x14000
	ds_read_b128 v[146:149], v140
	ds_read_b128 v[150:153], v140 offset:1024
	ds_read_b128 v[154:157], v140 offset:2048
	ds_read_b128 v[158:161], v140 offset:3072
	v_add_u32_e32 v140, s56, v143
	ds_read_b128 v[162:165], v140
	ds_read_b128 v[166:169], v140 offset:1024
	ds_read_b128 v[170:173], v140 offset:2048
	ds_read_b128 v[178:181], v140 offset:3072
	v_lshl_add_u64 v[140:141], s[18:19], 0, v[136:137]
	s_add_i32 m0, s39, 0xc000
	ds_read_b128 v[190:193], v145
	ds_read_b128 v[194:197], v145 offset:1024
	ds_read_b128 v[198:201], v145 offset:2048
	ds_read_b128 v[202:205], v145 offset:3072
	ds_read_b128 v[206:209], v145 offset:4096
	ds_read_b128 v[228:231], v145 offset:5120
	ds_read_b128 v[232:235], v145 offset:6144
	ds_read_b128 v[236:239], v145 offset:7168
	global_load_lds_dwordx4 v[140:141], off
	s_add_i32 m0, s39, 0xe000
	v_lshl_add_u64 v[140:141], s[18:19], 0, v[138:139]
	global_load_lds_dwordx4 v[140:141], off
	s_cmp_eq_u32 s52, -2
	s_cbranch_scc1 .Lz0_1_0
	s_setprio 1
	s_waitcnt vmcnt(8)
	s_waitcnt lgkmcnt(0)
	s_barrier
	v_mfma_f32_16x16x32_bf16 v[126:129], v[146:149], v[190:193], v[126:129]
	v_mfma_f32_16x16x32_bf16 v[126:129], v[150:153], v[194:197], v[126:129]
	v_mfma_f32_16x16x32_bf16 v[118:121], v[150:153], v[202:205], v[118:121]
	v_mfma_f32_16x16x32_bf16 v[118:121], v[146:149], v[198:201], v[118:121]
	v_mfma_f32_16x16x32_bf16 v[102:105], v[146:149], v[206:209], v[102:105]
	v_mfma_f32_16x16x32_bf16 v[102:105], v[150:153], v[228:231], v[102:105]
	v_mfma_f32_16x16x32_bf16 v[86:89], v[150:153], v[236:239], v[86:89]
	v_mfma_f32_16x16x32_bf16 v[86:89], v[146:149], v[232:235], v[86:89]
	v_mfma_f32_16x16x32_bf16 v[78:81], v[154:157], v[232:235], v[78:81]
	v_mfma_f32_16x16x32_bf16 v[78:81], v[158:161], v[236:239], v[78:81]
	v_mfma_f32_16x16x32_bf16 v[94:97], v[158:161], v[228:231], v[94:97]
	v_mfma_f32_16x16x32_bf16 v[94:97], v[154:157], v[206:209], v[94:97]
	v_mfma_f32_16x16x32_bf16 v[110:113], v[154:157], v[198:201], v[110:113]
	v_mfma_f32_16x16x32_bf16 v[110:113], v[158:161], v[202:205], v[110:113]
	v_mfma_f32_16x16x32_bf16 v[122:125], v[158:161], v[194:197], v[122:125]
	v_mfma_f32_16x16x32_bf16 v[122:125], v[154:157], v[190:193], v[122:125]
	v_mfma_f32_16x16x32_bf16 v[114:117], v[162:165], v[190:193], v[114:117]
	v_mfma_f32_16x16x32_bf16 v[114:117], v[166:169], v[194:197], v[114:117]
	v_mfma_f32_16x16x32_bf16 v[98:101], v[166:169], v[202:205], v[98:101]
	v_mfma_f32_16x16x32_bf16 v[98:101], v[162:165], v[198:201], v[98:101]
	v_mfma_f32_16x16x32_bf16 v[82:85], v[162:165], v[206:209], v[82:85]
	v_mfma_f32_16x16x32_bf16 v[82:85], v[166:169], v[228:231], v[82:85]
	v_mfma_f32_16x16x32_bf16 v[70:73], v[166:169], v[236:239], v[70:73]
	v_mfma_f32_16x16x32_bf16 v[70:73], v[162:165], v[232:235], v[70:73]
	v_mfma_f32_16x16x32_bf16 v[66:69], v[170:173], v[232:235], v[66:69]
	v_mfma_f32_16x16x32_bf16 v[66:69], v[178:181], v[236:239], v[66:69]
	v_mfma_f32_16x16x32_bf16 v[74:77], v[178:181], v[228:231], v[74:77]
	v_mfma_f32_16x16x32_bf16 v[74:77], v[170:173], v[206:209], v[74:77]
	v_mfma_f32_16x16x32_bf16 v[90:93], v[170:173], v[198:201], v[90:93]
	v_mfma_f32_16x16x32_bf16 v[90:93], v[178:181], v[202:205], v[90:93]
	v_mfma_f32_16x16x32_bf16 v[106:109], v[178:181], v[194:197], v[106:109]
	v_mfma_f32_16x16x32_bf16 v[106:109], v[170:173], v[190:193], v[106:109]
	s_barrier
	s_setprio 0
.Lz0_1_0_ret:
	s_add_i32 s53, s53, s38
	s_mov_b32 m0, s53
	v_lshl_add_u64 v[140:141], s[22:23], 0, v[0:1]
	global_load_lds_dwordx4 v[140:141], off
	ds_read_b128 v[190:193], v145 offset:16384
	ds_read_b128 v[194:197], v145 offset:17408
	s_add_i32 m0, s53, 0x2000
	s_add_u32 s54, s22, 0x100000
	v_lshl_add_u64 v[186:187], s[22:23], 0, v[130:131]
	s_addc_u32 s55, s23, 0
	s_add_i32 s53, s56, s38
	global_load_lds_dwordx4 v[186:187], off
	ds_read_b128 v[198:201], v145 offset:18432
	ds_read_b128 v[202:205], v145 offset:19456
	v_lshl_add_u64 v[188:189], s[54:55], 0, v[0:1]
	s_mov_b32 m0, s53
	v_lshl_add_u64 v[210:211], s[24:25], 0, v[132:133]
	global_load_lds_dwordx4 v[188:189], off
	ds_read_b128 v[206:209], v145 offset:20480
	ds_read_b128 v[228:231], v145 offset:21504
	s_add_i32 m0, s53, 0x2000
	v_lshl_add_u64 v[188:189], s[54:55], 0, v[130:131]
	global_load_lds_dwordx4 v[188:189], off
	ds_read_b128 v[232:235], v145 offset:22528
	ds_read_b128 v[236:239], v145 offset:23552
	s_mov_b32 m0, s39
	v_lshl_add_u64 v[188:189], s[24:25], 0, v[134:135]
	global_load_lds_dwordx4 v[188:189], off
	s_mov_b32 m0, s40
	s_nop 0
	global_load_lds_dwordx4 v[210:211], off
	s_cmp_eq_u32 s52, -2
	s_cbranch_scc1 .Lz0_1_1
	s_setprio 1
	s_waitcnt vmcnt(8)
	s_waitcnt lgkmcnt(0)
	s_barrier
	v_mfma_f32_16x16x32_bf16 v[62:65], v[146:149], v[190:193], v[62:65]
	v_mfma_f32_16x16x32_bf16 v[62:65], v[150:153], v[194:197], v[62:65]
	v_mfma_f32_16x16x32_bf16 v[54:57], v[150:153], v[202:205], v[54:57]
	v_mfma_f32_16x16x32_bf16 v[54:57], v[146:149], v[198:201], v[54:57]
	v_mfma_f32_16x16x32_bf16 v[38:41], v[146:149], v[206:209], v[38:41]
	v_mfma_f32_16x16x32_bf16 v[38:41], v[150:153], v[228:231], v[38:41]
	v_mfma_f32_16x16x32_bf16 v[22:25], v[150:153], v[236:239], v[22:25]
	v_mfma_f32_16x16x32_bf16 v[22:25], v[146:149], v[232:235], v[22:25]
	v_mfma_f32_16x16x32_bf16 v[14:17], v[154:157], v[232:235], v[14:17]
	v_mfma_f32_16x16x32_bf16 v[14:17], v[158:161], v[236:239], v[14:17]
	v_mfma_f32_16x16x32_bf16 v[30:33], v[158:161], v[228:231], v[30:33]
	v_mfma_f32_16x16x32_bf16 v[30:33], v[154:157], v[206:209], v[30:33]
	v_mfma_f32_16x16x32_bf16 v[46:49], v[154:157], v[198:201], v[46:49]
	v_mfma_f32_16x16x32_bf16 v[46:49], v[158:161], v[202:205], v[46:49]
	v_mfma_f32_16x16x32_bf16 v[58:61], v[158:161], v[194:197], v[58:61]
	v_mfma_f32_16x16x32_bf16 v[58:61], v[154:157], v[190:193], v[58:61]
	v_mfma_f32_16x16x32_bf16 v[50:53], v[162:165], v[190:193], v[50:53]
	v_mfma_f32_16x16x32_bf16 v[50:53], v[166:169], v[194:197], v[50:53]
	v_mfma_f32_16x16x32_bf16 v[34:37], v[166:169], v[202:205], v[34:37]
	v_mfma_f32_16x16x32_bf16 v[34:37], v[162:165], v[198:201], v[34:37]
	v_mfma_f32_16x16x32_bf16 v[18:21], v[162:165], v[206:209], v[18:21]
	v_mfma_f32_16x16x32_bf16 v[18:21], v[166:169], v[228:231], v[18:21]
	v_mfma_f32_16x16x32_bf16 v[6:9], v[166:169], v[236:239], v[6:9]
	v_mfma_f32_16x16x32_bf16 v[6:9], v[162:165], v[232:235], v[6:9]
	v_mfma_f32_16x16x32_bf16 v[2:5], v[170:173], v[232:235], v[2:5]
	v_mfma_f32_16x16x32_bf16 v[2:5], v[178:181], v[236:239], v[2:5]
	v_mfma_f32_16x16x32_bf16 v[10:13], v[178:181], v[228:231], v[10:13]
	v_mfma_f32_16x16x32_bf16 v[10:13], v[170:173], v[206:209], v[10:13]
	v_mfma_f32_16x16x32_bf16 v[26:29], v[170:173], v[198:201], v[26:29]
	v_mfma_f32_16x16x32_bf16 v[26:29], v[178:181], v[202:205], v[26:29]
	v_mfma_f32_16x16x32_bf16 v[42:45], v[178:181], v[194:197], v[42:45]
	v_mfma_f32_16x16x32_bf16 v[42:45], v[170:173], v[190:193], v[42:45]
	s_barrier
	s_setprio 0
.Lz0_1_1_ret:
	s_add_i32 s53, 0, 0x18000
	s_add_i32 s54, 0, 0x1c000
	v_add_u32_e32 v158, s53, v143
	v_add_u32_e32 v175, s54, v143
	ds_read_b128 v[146:149], v158
	ds_read_b128 v[150:153], v158 offset:1024
	ds_read_b128 v[154:157], v158 offset:2048
	ds_read_b128 v[158:161], v158 offset:3072
	ds_read_b128 v[162:165], v175
	ds_read_b128 v[166:169], v175 offset:1024
	ds_read_b128 v[170:173], v175 offset:2048
	ds_read_b128 v[178:181], v175 offset:3072
	s_add_u32 s24, s24, 0x100000
	s_addc_u32 s25, s25, 0
	s_mov_b32 m0, s41
	v_lshl_add_u64 v[226:227], s[24:25], 0, v[134:135]
	ds_read_b128 v[190:193], v145 offset:32768
	ds_read_b128 v[194:197], v145 offset:33792
	ds_read_b128 v[198:201], v145 offset:34816
	ds_read_b128 v[202:205], v145 offset:35840
	ds_read_b128 v[206:209], v145 offset:36864
	ds_read_b128 v[228:231], v145 offset:37888
	ds_read_b128 v[232:235], v145 offset:38912
	ds_read_b128 v[236:239], v145 offset:39936
	global_load_lds_dwordx4 v[226:227], off
	s_mov_b32 m0, s42
	v_lshl_add_u64 v[226:227], s[24:25], 0, v[132:133]
	global_load_lds_dwordx4 v[226:227], off
	s_setprio 1
	s_waitcnt vmcnt(8)
	s_waitcnt lgkmcnt(0)
	s_barrier
	v_mfma_f32_16x16x32_bf16 v[126:129], v[146:149], v[190:193], v[126:129]
	v_mfma_f32_16x16x32_bf16 v[126:129], v[150:153], v[194:197], v[126:129]
	v_mfma_f32_16x16x32_bf16 v[118:121], v[150:153], v[202:205], v[118:121]
	v_mfma_f32_16x16x32_bf16 v[118:121], v[146:149], v[198:201], v[118:121]
	v_mfma_f32_16x16x32_bf16 v[102:105], v[146:149], v[206:209], v[102:105]
	v_mfma_f32_16x16x32_bf16 v[102:105], v[150:153], v[228:231], v[102:105]
	v_mfma_f32_16x16x32_bf16 v[86:89], v[150:153], v[236:239], v[86:89]
	v_mfma_f32_16x16x32_bf16 v[86:89], v[146:149], v[232:235], v[86:89]
	v_mfma_f32_16x16x32_bf16 v[78:81], v[154:157], v[232:235], v[78:81]
	v_mfma_f32_16x16x32_bf16 v[78:81], v[158:161], v[236:239], v[78:81]
	v_mfma_f32_16x16x32_bf16 v[94:97], v[158:161], v[228:231], v[94:97]
	v_mfma_f32_16x16x32_bf16 v[94:97], v[154:157], v[206:209], v[94:97]
	v_mfma_f32_16x16x32_bf16 v[110:113], v[154:157], v[198:201], v[110:113]
	v_mfma_f32_16x16x32_bf16 v[110:113], v[158:161], v[202:205], v[110:113]
	v_mfma_f32_16x16x32_bf16 v[122:125], v[158:161], v[194:197], v[122:125]
	v_mfma_f32_16x16x32_bf16 v[122:125], v[154:157], v[190:193], v[122:125]
	v_mfma_f32_16x16x32_bf16 v[114:117], v[162:165], v[190:193], v[114:117]
	v_mfma_f32_16x16x32_bf16 v[114:117], v[166:169], v[194:197], v[114:117]
	v_mfma_f32_16x16x32_bf16 v[98:101], v[166:169], v[202:205], v[98:101]
	v_mfma_f32_16x16x32_bf16 v[98:101], v[162:165], v[198:201], v[98:101]
	v_mfma_f32_16x16x32_bf16 v[82:85], v[162:165], v[206:209], v[82:85]
	v_mfma_f32_16x16x32_bf16 v[82:85], v[166:169], v[228:231], v[82:85]
	v_mfma_f32_16x16x32_bf16 v[70:73], v[166:169], v[236:239], v[70:73]
	v_mfma_f32_16x16x32_bf16 v[70:73], v[162:165], v[232:235], v[70:73]
	v_mfma_f32_16x16x32_bf16 v[66:69], v[170:173], v[232:235], v[66:69]
	v_mfma_f32_16x16x32_bf16 v[66:69], v[178:181], v[236:239], v[66:69]
	v_mfma_f32_16x16x32_bf16 v[74:77], v[178:181], v[228:231], v[74:77]
	v_mfma_f32_16x16x32_bf16 v[74:77], v[170:173], v[206:209], v[74:77]
	v_mfma_f32_16x16x32_bf16 v[90:93], v[170:173], v[198:201], v[90:93]
	v_mfma_f32_16x16x32_bf16 v[90:93], v[178:181], v[202:205], v[90:93]
	v_mfma_f32_16x16x32_bf16 v[106:109], v[178:181], v[194:197], v[106:109]
	v_mfma_f32_16x16x32_bf16 v[106:109], v[170:173], v[190:193], v[106:109]
	s_barrier
	s_setprio 0
	s_add_i32 s24, s53, s38
	s_mov_b32 m0, s24
	v_lshl_add_u64 v[140:141], v[140:141], 0, s[34:35]
	global_load_lds_dwordx4 v[140:141], off
	ds_read_b128 v[190:193], v145 offset:49152
	ds_read_b128 v[194:197], v145 offset:50176
	s_add_i32 m0, s24, 0x2000
	s_add_u32 s22, s22, 0x100080
	v_lshl_add_u64 v[140:141], v[186:187], 0, s[34:35]
	s_addc_u32 s23, s23, 0
	s_add_i32 s24, s54, s38
	global_load_lds_dwordx4 v[140:141], off
	ds_read_b128 v[198:201], v145 offset:51200
	ds_read_b128 v[202:205], v145 offset:52224
	s_mov_b32 m0, s24
	v_lshl_add_u64 v[140:141], s[22:23], 0, v[0:1]
	global_load_lds_dwordx4 v[140:141], off
	ds_read_b128 v[206:209], v145 offset:53248
	ds_read_b128 v[228:231], v145 offset:54272
	s_add_i32 m0, s24, 0x2000
	v_lshl_add_u64 v[140:141], s[22:23], 0, v[130:131]
	global_load_lds_dwordx4 v[140:141], off
	ds_read_b128 v[232:235], v145 offset:55296
	ds_read_b128 v[236:239], v145 offset:56320
	s_mov_b32 m0, s43
	v_lshl_add_u64 v[140:141], v[188:189], 0, s[34:35]
	global_load_lds_dwordx4 v[140:141], off
	s_add_i32 s52, s52, 2
	s_add_u32 s18, s18, 0x100
	s_addc_u32 s19, s19, 0
	s_add_u32 s50, s50, 0x100
	s_addc_u32 s51, s51, 0
	s_add_u32 s22, s18, 0xfff00080
	s_addc_u32 s23, s19, -1
	s_cmp_eq_u32 s52, 60
	s_cselect_b32 s25, s9, s23
	s_cselect_b32 s24, s48, s22
	s_cselect_b32 s23, s7, s51
	s_cselect_b32 s22, s49, s50
	s_mov_b32 m0, s44
	v_lshl_add_u64 v[140:141], v[210:211], 0, s[34:35]
	global_load_lds_dwordx4 v[140:141], off
	s_setprio 1
	s_waitcnt vmcnt(8)
	s_waitcnt lgkmcnt(0)
	s_barrier
	v_mfma_f32_16x16x32_bf16 v[62:65], v[146:149], v[190:193], v[62:65]
	v_mfma_f32_16x16x32_bf16 v[62:65], v[150:153], v[194:197], v[62:65]
	v_mfma_f32_16x16x32_bf16 v[54:57], v[150:153], v[202:205], v[54:57]
	v_mfma_f32_16x16x32_bf16 v[54:57], v[146:149], v[198:201], v[54:57]
	v_mfma_f32_16x16x32_bf16 v[38:41], v[146:149], v[206:209], v[38:41]
	v_mfma_f32_16x16x32_bf16 v[38:41], v[150:153], v[228:231], v[38:41]
	v_mfma_f32_16x16x32_bf16 v[22:25], v[150:153], v[236:239], v[22:25]
	v_mfma_f32_16x16x32_bf16 v[22:25], v[146:149], v[232:235], v[22:25]
	v_mfma_f32_16x16x32_bf16 v[14:17], v[154:157], v[232:235], v[14:17]
	v_mfma_f32_16x16x32_bf16 v[14:17], v[158:161], v[236:239], v[14:17]
	v_mfma_f32_16x16x32_bf16 v[30:33], v[158:161], v[228:231], v[30:33]
	v_mfma_f32_16x16x32_bf16 v[30:33], v[154:157], v[206:209], v[30:33]
	v_mfma_f32_16x16x32_bf16 v[46:49], v[154:157], v[198:201], v[46:49]
	v_mfma_f32_16x16x32_bf16 v[46:49], v[158:161], v[202:205], v[46:49]
	v_mfma_f32_16x16x32_bf16 v[58:61], v[158:161], v[194:197], v[58:61]
	v_mfma_f32_16x16x32_bf16 v[58:61], v[154:157], v[190:193], v[58:61]
	v_mfma_f32_16x16x32_bf16 v[50:53], v[162:165], v[190:193], v[50:53]
	v_mfma_f32_16x16x32_bf16 v[50:53], v[166:169], v[194:197], v[50:53]
	v_mfma_f32_16x16x32_bf16 v[34:37], v[166:169], v[202:205], v[34:37]
	v_mfma_f32_16x16x32_bf16 v[34:37], v[162:165], v[198:201], v[34:37]
	v_mfma_f32_16x16x32_bf16 v[18:21], v[162:165], v[206:209], v[18:21]
	v_mfma_f32_16x16x32_bf16 v[18:21], v[166:169], v[228:231], v[18:21]
	v_mfma_f32_16x16x32_bf16 v[6:9], v[166:169], v[236:239], v[6:9]
	v_mfma_f32_16x16x32_bf16 v[6:9], v[162:165], v[232:235], v[6:9]
	v_mfma_f32_16x16x32_bf16 v[2:5], v[170:173], v[232:235], v[2:5]
	v_mfma_f32_16x16x32_bf16 v[2:5], v[178:181], v[236:239], v[2:5]
	v_mfma_f32_16x16x32_bf16 v[10:13], v[178:181], v[228:231], v[10:13]
	v_mfma_f32_16x16x32_bf16 v[10:13], v[170:173], v[206:209], v[10:13]
	v_mfma_f32_16x16x32_bf16 v[26:29], v[170:173], v[198:201], v[26:29]
	v_mfma_f32_16x16x32_bf16 v[26:29], v[178:181], v[202:205], v[26:29]
	v_mfma_f32_16x16x32_bf16 v[42:45], v[178:181], v[194:197], v[42:45]
	v_mfma_f32_16x16x32_bf16 v[42:45], v[170:173], v[190:193], v[42:45]
	s_barrier
	s_setprio 0
	s_cmp_gt_u32 s52, 61
	s_cbranch_scc0 .LBB0_575
	s_and_b64 vcc, exec, s[4:5]
	s_cbranch_vccz .LBB0_578
	s_barrier

.LBB0_721:
	s_add_i32 s53, 0, 0x10000
	v_add_u32_e32 v140, s53, v143
	s_add_i32 s56, 0, 0x14000
	ds_read_b128 v[146:149], v140
	ds_read_b128 v[150:153], v140 offset:1024
	ds_read_b128 v[154:157], v140 offset:2048
	ds_read_b128 v[158:161], v140 offset:3072
	v_add_u32_e32 v140, s56, v143
	ds_read_b128 v[162:165], v140
	ds_read_b128 v[166:169], v140 offset:1024
	ds_read_b128 v[170:173], v140 offset:2048
	ds_read_b128 v[178:181], v140 offset:3072
	v_lshl_add_u64 v[140:141], s[16:17], 0, v[136:137]
	s_add_i32 m0, s31, 0xc000
	ds_read_b128 v[190:193], v145
	ds_read_b128 v[194:197], v145 offset:1024
	ds_read_b128 v[198:201], v145 offset:2048
	ds_read_b128 v[202:205], v145 offset:3072
	ds_read_b128 v[206:209], v145 offset:4096
	ds_read_b128 v[228:231], v145 offset:5120
	ds_read_b128 v[232:235], v145 offset:6144
	ds_read_b128 v[236:239], v145 offset:7168
	global_load_lds_dwordx4 v[140:141], off
	s_add_i32 m0, s31, 0xe000
	v_lshl_add_u64 v[140:141], s[16:17], 0, v[138:139]
	global_load_lds_dwordx4 v[140:141], off
	s_cmp_eq_u32 s52, -2
	s_cbranch_scc1 .Lz0_2_0
	s_setprio 1
	s_waitcnt vmcnt(8)
	s_waitcnt lgkmcnt(0)
	s_barrier
	v_mfma_f32_16x16x32_bf16 v[126:129], v[146:149], v[190:193], v[126:129]
	v_mfma_f32_16x16x32_bf16 v[126:129], v[150:153], v[194:197], v[126:129]
	v_mfma_f32_16x16x32_bf16 v[110:113], v[150:153], v[202:205], v[110:113]
	v_mfma_f32_16x16x32_bf16 v[110:113], v[146:149], v[198:201], v[110:113]
	v_mfma_f32_16x16x32_bf16 v[94:97], v[146:149], v[206:209], v[94:97]
	v_mfma_f32_16x16x32_bf16 v[94:97], v[150:153], v[228:231], v[94:97]
	v_mfma_f32_16x16x32_bf16 v[78:81], v[150:153], v[236:239], v[78:81]
	v_mfma_f32_16x16x32_bf16 v[78:81], v[146:149], v[232:235], v[78:81]
	v_mfma_f32_16x16x32_bf16 v[70:73], v[154:157], v[232:235], v[70:73]
	v_mfma_f32_16x16x32_bf16 v[70:73], v[158:161], v[236:239], v[70:73]
	v_mfma_f32_16x16x32_bf16 v[86:89], v[158:161], v[228:231], v[86:89]
	v_mfma_f32_16x16x32_bf16 v[86:89], v[154:157], v[206:209], v[86:89]
	v_mfma_f32_16x16x32_bf16 v[102:105], v[154:157], v[198:201], v[102:105]
	v_mfma_f32_16x16x32_bf16 v[102:105], v[158:161], v[202:205], v[102:105]
	v_mfma_f32_16x16x32_bf16 v[118:121], v[158:161], v[194:197], v[118:121]
	v_mfma_f32_16x16x32_bf16 v[118:121], v[154:157], v[190:193], v[118:121]
	v_mfma_f32_16x16x32_bf16 v[122:125], v[162:165], v[190:193], v[122:125]
	v_mfma_f32_16x16x32_bf16 v[122:125], v[166:169], v[194:197], v[122:125]
	v_mfma_f32_16x16x32_bf16 v[106:109], v[166:169], v[202:205], v[106:109]
	v_mfma_f32_16x16x32_bf16 v[106:109], v[162:165], v[198:201], v[106:109]
	v_mfma_f32_16x16x32_bf16 v[90:93], v[162:165], v[206:209], v[90:93]
	v_mfma_f32_16x16x32_bf16 v[90:93], v[166:169], v[228:231], v[90:93]
	v_mfma_f32_16x16x32_bf16 v[74:77], v[166:169], v[236:239], v[74:77]
	v_mfma_f32_16x16x32_bf16 v[74:77], v[162:165], v[232:235], v[74:77]
	v_mfma_f32_16x16x32_bf16 v[66:69], v[170:173], v[232:235], v[66:69]
	v_mfma_f32_16x16x32_bf16 v[66:69], v[178:181], v[236:239], v[66:69]
	v_mfma_f32_16x16x32_bf16 v[82:85], v[178:181], v[228:231], v[82:85]
	v_mfma_f32_16x16x32_bf16 v[82:85], v[170:173], v[206:209], v[82:85]
	v_mfma_f32_16x16x32_bf16 v[98:101], v[170:173], v[198:201], v[98:101]
	v_mfma_f32_16x16x32_bf16 v[98:101], v[178:181], v[202:205], v[98:101]
	v_mfma_f32_16x16x32_bf16 v[114:117], v[178:181], v[194:197], v[114:117]
	v_mfma_f32_16x16x32_bf16 v[114:117], v[170:173], v[190:193], v[114:117]
	s_barrier
	s_setprio 0
.Lz0_2_0_ret:
	s_add_i32 s53, s53, s26
	s_mov_b32 m0, s53
	v_lshl_add_u64 v[140:141], s[18:19], 0, v[0:1]
	global_load_lds_dwordx4 v[140:141], off
	ds_read_b128 v[190:193], v145 offset:16384
	ds_read_b128 v[194:197], v145 offset:17408
	s_add_i32 m0, s53, 0x2000
	s_add_u32 s54, s18, 0x100000
	v_lshl_add_u64 v[186:187], s[18:19], 0, v[130:131]
	s_addc_u32 s55, s19, 0
	s_add_i32 s53, s56, s26
	global_load_lds_dwordx4 v[186:187], off
	ds_read_b128 v[198:201], v145 offset:18432
	ds_read_b128 v[202:205], v145 offset:19456
	v_lshl_add_u64 v[188:189], s[54:55], 0, v[0:1]
	s_mov_b32 m0, s53
	v_lshl_add_u64 v[210:211], s[22:23], 0, v[132:133]
	global_load_lds_dwordx4 v[188:189], off
	ds_read_b128 v[206:209], v145 offset:20480
	ds_read_b128 v[228:231], v145 offset:21504
	s_add_i32 m0, s53, 0x2000
	v_lshl_add_u64 v[188:189], s[54:55], 0, v[130:131]
	global_load_lds_dwordx4 v[188:189], off
	ds_read_b128 v[232:235], v145 offset:22528
	ds_read_b128 v[236:239], v145 offset:23552
	s_mov_b32 m0, s31
	v_lshl_add_u64 v[188:189], s[22:23], 0, v[134:135]
	global_load_lds_dwordx4 v[188:189], off
	s_mov_b32 m0, s40
	s_nop 0
	global_load_lds_dwordx4 v[210:211], off
	s_cmp_eq_u32 s52, -2
	s_cbranch_scc1 .Lz0_2_1
	s_setprio 1
	s_waitcnt vmcnt(8)
	s_waitcnt lgkmcnt(0)
	s_barrier
	v_mfma_f32_16x16x32_bf16 v[62:65], v[146:149], v[190:193], v[62:65]
	v_mfma_f32_16x16x32_bf16 v[62:65], v[150:153], v[194:197], v[62:65]
	v_mfma_f32_16x16x32_bf16 v[46:49], v[150:153], v[202:205], v[46:49]
	v_mfma_f32_16x16x32_bf16 v[46:49], v[146:149], v[198:201], v[46:49]
	v_mfma_f32_16x16x32_bf16 v[30:33], v[146:149], v[206:209], v[30:33]
	v_mfma_f32_16x16x32_bf16 v[30:33], v[150:153], v[228:231], v[30:33]
	v_mfma_f32_16x16x32_bf16 v[14:17], v[150:153], v[236:239], v[14:17]
	v_mfma_f32_16x16x32_bf16 v[14:17], v[146:149], v[232:235], v[14:17]
	v_mfma_f32_16x16x32_bf16 v[6:9], v[154:157], v[232:235], v[6:9]
	v_mfma_f32_16x16x32_bf16 v[6:9], v[158:161], v[236:239], v[6:9]
	v_mfma_f32_16x16x32_bf16 v[22:25], v[158:161], v[228:231], v[22:25]
	v_mfma_f32_16x16x32_bf16 v[22:25], v[154:157], v[206:209], v[22:25]
	v_mfma_f32_16x16x32_bf16 v[38:41], v[154:157], v[198:201], v[38:41]
	v_mfma_f32_16x16x32_bf16 v[38:41], v[158:161], v[202:205], v[38:41]
	v_mfma_f32_16x16x32_bf16 v[54:57], v[158:161], v[194:197], v[54:57]
	v_mfma_f32_16x16x32_bf16 v[54:57], v[154:157], v[190:193], v[54:57]
	v_mfma_f32_16x16x32_bf16 v[58:61], v[162:165], v[190:193], v[58:61]
	v_mfma_f32_16x16x32_bf16 v[58:61], v[166:169], v[194:197], v[58:61]
	v_mfma_f32_16x16x32_bf16 v[42:45], v[166:169], v[202:205], v[42:45]
	v_mfma_f32_16x16x32_bf16 v[42:45], v[162:165], v[198:201], v[42:45]
	v_mfma_f32_16x16x32_bf16 v[26:29], v[162:165], v[206:209], v[26:29]
	v_mfma_f32_16x16x32_bf16 v[26:29], v[166:169], v[228:231], v[26:29]
	v_mfma_f32_16x16x32_bf16 v[10:13], v[166:169], v[236:239], v[10:13]
	v_mfma_f32_16x16x32_bf16 v[10:13], v[162:165], v[232:235], v[10:13]
	v_mfma_f32_16x16x32_bf16 v[2:5], v[170:173], v[232:235], v[2:5]
	v_mfma_f32_16x16x32_bf16 v[2:5], v[178:181], v[236:239], v[2:5]
	v_mfma_f32_16x16x32_bf16 v[18:21], v[178:181], v[228:231], v[18:21]
	v_mfma_f32_16x16x32_bf16 v[18:21], v[170:173], v[206:209], v[18:21]
	v_mfma_f32_16x16x32_bf16 v[34:37], v[170:173], v[198:201], v[34:37]
	v_mfma_f32_16x16x32_bf16 v[34:37], v[178:181], v[202:205], v[34:37]
	v_mfma_f32_16x16x32_bf16 v[50:53], v[178:181], v[194:197], v[50:53]
	v_mfma_f32_16x16x32_bf16 v[50:53], v[170:173], v[190:193], v[50:53]
	s_barrier
	s_setprio 0
.Lz0_2_1_ret:
	s_add_i32 s53, 0, 0x18000
	s_add_i32 s54, 0, 0x1c000
	v_add_u32_e32 v158, s53, v143
	v_add_u32_e32 v175, s54, v143
	ds_read_b128 v[146:149], v158
	ds_read_b128 v[150:153], v158 offset:1024
	ds_read_b128 v[154:157], v158 offset:2048
	ds_read_b128 v[158:161], v158 offset:3072
	ds_read_b128 v[162:165], v175
	ds_read_b128 v[166:169], v175 offset:1024
	ds_read_b128 v[170:173], v175 offset:2048
	ds_read_b128 v[178:181], v175 offset:3072
	s_add_u32 s22, s22, 0x100000
	s_addc_u32 s23, s23, 0
	s_mov_b32 m0, s41
	v_lshl_add_u64 v[226:227], s[22:23], 0, v[134:135]
	ds_read_b128 v[190:193], v145 offset:32768
	ds_read_b128 v[194:197], v145 offset:33792
	ds_read_b128 v[198:201], v145 offset:34816
	ds_read_b128 v[202:205], v145 offset:35840
	ds_read_b128 v[206:209], v145 offset:36864
	ds_read_b128 v[228:231], v145 offset:37888
	ds_read_b128 v[232:235], v145 offset:38912
	ds_read_b128 v[236:239], v145 offset:39936
	global_load_lds_dwordx4 v[226:227], off
	s_mov_b32 m0, s42
	v_lshl_add_u64 v[226:227], s[22:23], 0, v[132:133]
	global_load_lds_dwordx4 v[226:227], off
	s_setprio 1
	s_waitcnt vmcnt(8)
	s_waitcnt lgkmcnt(0)
	s_barrier
	v_mfma_f32_16x16x32_bf16 v[126:129], v[146:149], v[190:193], v[126:129]
	v_mfma_f32_16x16x32_bf16 v[126:129], v[150:153], v[194:197], v[126:129]
	v_mfma_f32_16x16x32_bf16 v[110:113], v[150:153], v[202:205], v[110:113]
	v_mfma_f32_16x16x32_bf16 v[110:113], v[146:149], v[198:201], v[110:113]
	v_mfma_f32_16x16x32_bf16 v[94:97], v[146:149], v[206:209], v[94:97]
	v_mfma_f32_16x16x32_bf16 v[94:97], v[150:153], v[228:231], v[94:97]
	v_mfma_f32_16x16x32_bf16 v[78:81], v[150:153], v[236:239], v[78:81]
	v_mfma_f32_16x16x32_bf16 v[78:81], v[146:149], v[232:235], v[78:81]
	v_mfma_f32_16x16x32_bf16 v[70:73], v[154:157], v[232:235], v[70:73]
	v_mfma_f32_16x16x32_bf16 v[70:73], v[158:161], v[236:239], v[70:73]
	v_mfma_f32_16x16x32_bf16 v[86:89], v[158:161], v[228:231], v[86:89]
	v_mfma_f32_16x16x32_bf16 v[86:89], v[154:157], v[206:209], v[86:89]
	v_mfma_f32_16x16x32_bf16 v[102:105], v[154:157], v[198:201], v[102:105]
	v_mfma_f32_16x16x32_bf16 v[102:105], v[158:161], v[202:205], v[102:105]
	v_mfma_f32_16x16x32_bf16 v[118:121], v[158:161], v[194:197], v[118:121]
	v_mfma_f32_16x16x32_bf16 v[118:121], v[154:157], v[190:193], v[118:121]
	v_mfma_f32_16x16x32_bf16 v[122:125], v[162:165], v[190:193], v[122:125]
	v_mfma_f32_16x16x32_bf16 v[122:125], v[166:169], v[194:197], v[122:125]
	v_mfma_f32_16x16x32_bf16 v[106:109], v[166:169], v[202:205], v[106:109]
	v_mfma_f32_16x16x32_bf16 v[106:109], v[162:165], v[198:201], v[106:109]
	v_mfma_f32_16x16x32_bf16 v[90:93], v[162:165], v[206:209], v[90:93]
	v_mfma_f32_16x16x32_bf16 v[90:93], v[166:169], v[228:231], v[90:93]
	v_mfma_f32_16x16x32_bf16 v[74:77], v[166:169], v[236:239], v[74:77]
	v_mfma_f32_16x16x32_bf16 v[74:77], v[162:165], v[232:235], v[74:77]
	v_mfma_f32_16x16x32_bf16 v[66:69], v[170:173], v[232:235], v[66:69]
	v_mfma_f32_16x16x32_bf16 v[66:69], v[178:181], v[236:239], v[66:69]
	v_mfma_f32_16x16x32_bf16 v[82:85], v[178:181], v[228:231], v[82:85]
	v_mfma_f32_16x16x32_bf16 v[82:85], v[170:173], v[206:209], v[82:85]
	v_mfma_f32_16x16x32_bf16 v[98:101], v[170:173], v[198:201], v[98:101]
	v_mfma_f32_16x16x32_bf16 v[98:101], v[178:181], v[202:205], v[98:101]
	v_mfma_f32_16x16x32_bf16 v[114:117], v[178:181], v[194:197], v[114:117]
	v_mfma_f32_16x16x32_bf16 v[114:117], v[170:173], v[190:193], v[114:117]
	s_barrier
	s_setprio 0
	s_add_i32 s22, s53, s26
	s_mov_b32 m0, s22
	v_lshl_add_u64 v[140:141], v[140:141], 0, s[34:35]
	global_load_lds_dwordx4 v[140:141], off
	ds_read_b128 v[190:193], v145 offset:49152
	ds_read_b128 v[194:197], v145 offset:50176
	s_add_i32 m0, s22, 0x2000
	s_add_u32 s18, s18, 0x100080
	v_lshl_add_u64 v[140:141], v[186:187], 0, s[34:35]
	s_addc_u32 s19, s19, 0
	s_add_i32 s22, s54, s26
	global_load_lds_dwordx4 v[140:141], off
	ds_read_b128 v[198:201], v145 offset:51200
	ds_read_b128 v[202:205], v145 offset:52224
	s_mov_b32 m0, s22
	v_lshl_add_u64 v[140:141], s[18:19], 0, v[0:1]
	global_load_lds_dwordx4 v[140:141], off
	ds_read_b128 v[206:209], v145 offset:53248
	ds_read_b128 v[228:231], v145 offset:54272
	s_add_i32 m0, s22, 0x2000
	v_lshl_add_u64 v[140:141], s[18:19], 0, v[130:131]
	global_load_lds_dwordx4 v[140:141], off
	ds_read_b128 v[232:235], v145 offset:55296
	ds_read_b128 v[236:239], v145 offset:56320
	s_mov_b32 m0, s43
	v_lshl_add_u64 v[140:141], v[188:189], 0, s[34:35]
	global_load_lds_dwordx4 v[140:141], off
	s_add_i32 s52, s52, 2
	s_add_u32 s16, s16, 0x100
	s_addc_u32 s17, s17, 0
	s_add_u32 s50, s50, 0x100
	s_addc_u32 s51, s51, 0
	s_add_u32 s18, s16, 0xfff00080
	s_addc_u32 s19, s17, -1
	s_cmp_eq_u32 s52, 60
	s_cselect_b32 s23, s7, s19
	s_cselect_b32 s22, s48, s18
	s_cselect_b32 s19, s5, s51
	s_cselect_b32 s18, s49, s50
	s_mov_b32 m0, s44
	v_lshl_add_u64 v[140:141], v[210:211], 0, s[34:35]
	global_load_lds_dwordx4 v[140:141], off
	s_setprio 1
	s_waitcnt vmcnt(8)
	s_waitcnt lgkmcnt(0)
	s_barrier
	v_mfma_f32_16x16x32_bf16 v[62:65], v[146:149], v[190:193], v[62:65]
	v_mfma_f32_16x16x32_bf16 v[62:65], v[150:153], v[194:197], v[62:65]
	v_mfma_f32_16x16x32_bf16 v[46:49], v[150:153], v[202:205], v[46:49]
	v_mfma_f32_16x16x32_bf16 v[46:49], v[146:149], v[198:201], v[46:49]
	v_mfma_f32_16x16x32_bf16 v[30:33], v[146:149], v[206:209], v[30:33]
	v_mfma_f32_16x16x32_bf16 v[30:33], v[150:153], v[228:231], v[30:33]
	v_mfma_f32_16x16x32_bf16 v[14:17], v[150:153], v[236:239], v[14:17]
	v_mfma_f32_16x16x32_bf16 v[14:17], v[146:149], v[232:235], v[14:17]
	v_mfma_f32_16x16x32_bf16 v[6:9], v[154:157], v[232:235], v[6:9]
	v_mfma_f32_16x16x32_bf16 v[6:9], v[158:161], v[236:239], v[6:9]
	v_mfma_f32_16x16x32_bf16 v[22:25], v[158:161], v[228:231], v[22:25]
	v_mfma_f32_16x16x32_bf16 v[22:25], v[154:157], v[206:209], v[22:25]
	v_mfma_f32_16x16x32_bf16 v[38:41], v[154:157], v[198:201], v[38:41]
	v_mfma_f32_16x16x32_bf16 v[38:41], v[158:161], v[202:205], v[38:41]
	v_mfma_f32_16x16x32_bf16 v[54:57], v[158:161], v[194:197], v[54:57]
	v_mfma_f32_16x16x32_bf16 v[54:57], v[154:157], v[190:193], v[54:57]
	v_mfma_f32_16x16x32_bf16 v[58:61], v[162:165], v[190:193], v[58:61]
	v_mfma_f32_16x16x32_bf16 v[58:61], v[166:169], v[194:197], v[58:61]
	v_mfma_f32_16x16x32_bf16 v[42:45], v[166:169], v[202:205], v[42:45]
	v_mfma_f32_16x16x32_bf16 v[42:45], v[162:165], v[198:201], v[42:45]
	v_mfma_f32_16x16x32_bf16 v[26:29], v[162:165], v[206:209], v[26:29]
	v_mfma_f32_16x16x32_bf16 v[26:29], v[166:169], v[228:231], v[26:29]
	v_mfma_f32_16x16x32_bf16 v[10:13], v[166:169], v[236:239], v[10:13]
	v_mfma_f32_16x16x32_bf16 v[10:13], v[162:165], v[232:235], v[10:13]
	v_mfma_f32_16x16x32_bf16 v[2:5], v[170:173], v[232:235], v[2:5]
	v_mfma_f32_16x16x32_bf16 v[2:5], v[178:181], v[236:239], v[2:5]
	v_mfma_f32_16x16x32_bf16 v[18:21], v[178:181], v[228:231], v[18:21]
	v_mfma_f32_16x16x32_bf16 v[18:21], v[170:173], v[206:209], v[18:21]
	v_mfma_f32_16x16x32_bf16 v[34:37], v[170:173], v[198:201], v[34:37]
	v_mfma_f32_16x16x32_bf16 v[34:37], v[178:181], v[202:205], v[34:37]
	v_mfma_f32_16x16x32_bf16 v[50:53], v[178:181], v[194:197], v[50:53]
	v_mfma_f32_16x16x32_bf16 v[50:53], v[170:173], v[190:193], v[50:53]
	s_barrier
	s_setprio 0
	s_cmp_gt_u32 s52, 61
	s_cbranch_scc0 .LBB0_721
	s_and_b64 vcc, exec, s[2:3]
	s_cbranch_vccz .LBB0_724
	s_barrier

.LBB0_805:
	s_add_i32 s49, 0, 0x10000
	v_add_u32_e32 v140, s49, v143
	s_add_i32 s50, 0, 0x14000
	ds_read_b128 v[146:149], v140
	ds_read_b128 v[150:153], v140 offset:1024
	ds_read_b128 v[154:157], v140 offset:2048
	ds_read_b128 v[158:161], v140 offset:3072
	v_add_u32_e32 v140, s50, v143
	ds_read_b128 v[162:165], v140
	ds_read_b128 v[166:169], v140 offset:1024
	ds_read_b128 v[170:173], v140 offset:2048
	ds_read_b128 v[178:181], v140 offset:3072
	v_lshl_add_u64 v[140:141], s[14:15], 0, v[136:137]
	s_add_i32 m0, s31, 0xc000
	ds_read_b128 v[190:193], v145
	ds_read_b128 v[194:197], v145 offset:1024
	ds_read_b128 v[198:201], v145 offset:2048
	ds_read_b128 v[202:205], v145 offset:3072
	ds_read_b128 v[206:209], v145 offset:4096
	ds_read_b128 v[228:231], v145 offset:5120
	ds_read_b128 v[232:235], v145 offset:6144
	ds_read_b128 v[236:239], v145 offset:7168
	global_load_lds_dwordx4 v[140:141], off
	s_add_i32 m0, s31, 0xe000
	v_lshl_add_u64 v[140:141], s[14:15], 0, v[138:139]
	global_load_lds_dwordx4 v[140:141], off
	s_cmp_eq_u32 s48, -2
	s_cbranch_scc1 .Lz0_3_0
	s_setprio 1
	s_waitcnt vmcnt(8)
	s_waitcnt lgkmcnt(0)
	s_barrier
	v_mfma_f32_16x16x32_bf16 v[126:129], v[146:149], v[190:193], v[126:129]
	v_mfma_f32_16x16x32_bf16 v[126:129], v[150:153], v[194:197], v[126:129]
	v_mfma_f32_16x16x32_bf16 v[118:121], v[150:153], v[202:205], v[118:121]
	v_mfma_f32_16x16x32_bf16 v[118:121], v[146:149], v[198:201], v[118:121]
	v_mfma_f32_16x16x32_bf16 v[102:105], v[146:149], v[206:209], v[102:105]
	v_mfma_f32_16x16x32_bf16 v[102:105], v[150:153], v[228:231], v[102:105]
	v_mfma_f32_16x16x32_bf16 v[86:89], v[150:153], v[236:239], v[86:89]
	v_mfma_f32_16x16x32_bf16 v[86:89], v[146:149], v[232:235], v[86:89]
	v_mfma_f32_16x16x32_bf16 v[78:81], v[154:157], v[232:235], v[78:81]
	v_mfma_f32_16x16x32_bf16 v[78:81], v[158:161], v[236:239], v[78:81]
	v_mfma_f32_16x16x32_bf16 v[94:97], v[158:161], v[228:231], v[94:97]
	v_mfma_f32_16x16x32_bf16 v[94:97], v[154:157], v[206:209], v[94:97]
	v_mfma_f32_16x16x32_bf16 v[110:113], v[154:157], v[198:201], v[110:113]
	v_mfma_f32_16x16x32_bf16 v[110:113], v[158:161], v[202:205], v[110:113]
	v_mfma_f32_16x16x32_bf16 v[122:125], v[158:161], v[194:197], v[122:125]
	v_mfma_f32_16x16x32_bf16 v[122:125], v[154:157], v[190:193], v[122:125]
	v_mfma_f32_16x16x32_bf16 v[114:117], v[162:165], v[190:193], v[114:117]
	v_mfma_f32_16x16x32_bf16 v[114:117], v[166:169], v[194:197], v[114:117]
	v_mfma_f32_16x16x32_bf16 v[98:101], v[166:169], v[202:205], v[98:101]
	v_mfma_f32_16x16x32_bf16 v[98:101], v[162:165], v[198:201], v[98:101]
	v_mfma_f32_16x16x32_bf16 v[82:85], v[162:165], v[206:209], v[82:85]
	v_mfma_f32_16x16x32_bf16 v[82:85], v[166:169], v[228:231], v[82:85]
	v_mfma_f32_16x16x32_bf16 v[70:73], v[166:169], v[236:239], v[70:73]
	v_mfma_f32_16x16x32_bf16 v[70:73], v[162:165], v[232:235], v[70:73]
	v_mfma_f32_16x16x32_bf16 v[66:69], v[170:173], v[232:235], v[66:69]
	v_mfma_f32_16x16x32_bf16 v[66:69], v[178:181], v[236:239], v[66:69]
	v_mfma_f32_16x16x32_bf16 v[74:77], v[178:181], v[228:231], v[74:77]
	v_mfma_f32_16x16x32_bf16 v[74:77], v[170:173], v[206:209], v[74:77]
	v_mfma_f32_16x16x32_bf16 v[90:93], v[170:173], v[198:201], v[90:93]
	v_mfma_f32_16x16x32_bf16 v[90:93], v[178:181], v[202:205], v[90:93]
	v_mfma_f32_16x16x32_bf16 v[106:109], v[178:181], v[194:197], v[106:109]
	v_mfma_f32_16x16x32_bf16 v[106:109], v[170:173], v[190:193], v[106:109]
	s_barrier
	s_setprio 0
.Lz0_3_0_ret:
	s_add_i32 s14, s49, s26
	s_mov_b32 m0, s14
	v_lshl_add_u64 v[140:141], s[18:19], 0, v[0:1]
	global_load_lds_dwordx4 v[140:141], off
	ds_read_b128 v[190:193], v145 offset:16384
	ds_read_b128 v[194:197], v145 offset:17408
	s_add_i32 m0, s14, 0x2000
	s_add_u32 s14, s18, 0x2b0000
	v_lshl_add_u64 v[186:187], s[18:19], 0, v[130:131]
	s_addc_u32 s15, s19, 0
	s_add_i32 s49, s50, s26
	global_load_lds_dwordx4 v[186:187], off
	ds_read_b128 v[198:201], v145 offset:18432
	ds_read_b128 v[202:205], v145 offset:19456
	v_lshl_add_u64 v[188:189], s[14:15], 0, v[0:1]
	s_mov_b32 m0, s49
	v_lshl_add_u64 v[210:211], s[22:23], 0, v[132:133]
	global_load_lds_dwordx4 v[188:189], off
	ds_read_b128 v[206:209], v145 offset:20480
	ds_read_b128 v[228:231], v145 offset:21504
	s_add_i32 m0, s49, 0x2000
	v_lshl_add_u64 v[188:189], s[14:15], 0, v[130:131]
	global_load_lds_dwordx4 v[188:189], off
	ds_read_b128 v[232:235], v145 offset:22528
	ds_read_b128 v[236:239], v145 offset:23552
	s_mov_b32 m0, s31
	v_lshl_add_u64 v[188:189], s[22:23], 0, v[134:135]
	global_load_lds_dwordx4 v[188:189], off
	s_mov_b32 m0, s36
	s_nop 0
	global_load_lds_dwordx4 v[210:211], off
	s_cmp_eq_u32 s48, -2
	s_cbranch_scc1 .Lz0_3_1
	s_setprio 1
	s_waitcnt vmcnt(8)
	s_waitcnt lgkmcnt(0)
	s_barrier
	v_mfma_f32_16x16x32_bf16 v[62:65], v[146:149], v[190:193], v[62:65]
	v_mfma_f32_16x16x32_bf16 v[62:65], v[150:153], v[194:197], v[62:65]
	v_mfma_f32_16x16x32_bf16 v[54:57], v[150:153], v[202:205], v[54:57]
	v_mfma_f32_16x16x32_bf16 v[54:57], v[146:149], v[198:201], v[54:57]
	v_mfma_f32_16x16x32_bf16 v[38:41], v[146:149], v[206:209], v[38:41]
	v_mfma_f32_16x16x32_bf16 v[38:41], v[150:153], v[228:231], v[38:41]
	v_mfma_f32_16x16x32_bf16 v[22:25], v[150:153], v[236:239], v[22:25]
	v_mfma_f32_16x16x32_bf16 v[22:25], v[146:149], v[232:235], v[22:25]
	v_mfma_f32_16x16x32_bf16 v[14:17], v[154:157], v[232:235], v[14:17]
	v_mfma_f32_16x16x32_bf16 v[14:17], v[158:161], v[236:239], v[14:17]
	v_mfma_f32_16x16x32_bf16 v[30:33], v[158:161], v[228:231], v[30:33]
	v_mfma_f32_16x16x32_bf16 v[30:33], v[154:157], v[206:209], v[30:33]
	v_mfma_f32_16x16x32_bf16 v[46:49], v[154:157], v[198:201], v[46:49]
	v_mfma_f32_16x16x32_bf16 v[46:49], v[158:161], v[202:205], v[46:49]
	v_mfma_f32_16x16x32_bf16 v[58:61], v[158:161], v[194:197], v[58:61]
	v_mfma_f32_16x16x32_bf16 v[58:61], v[154:157], v[190:193], v[58:61]
	v_mfma_f32_16x16x32_bf16 v[50:53], v[162:165], v[190:193], v[50:53]
	v_mfma_f32_16x16x32_bf16 v[50:53], v[166:169], v[194:197], v[50:53]
	v_mfma_f32_16x16x32_bf16 v[34:37], v[166:169], v[202:205], v[34:37]
	v_mfma_f32_16x16x32_bf16 v[34:37], v[162:165], v[198:201], v[34:37]
	v_mfma_f32_16x16x32_bf16 v[18:21], v[162:165], v[206:209], v[18:21]
	v_mfma_f32_16x16x32_bf16 v[18:21], v[166:169], v[228:231], v[18:21]
	v_mfma_f32_16x16x32_bf16 v[6:9], v[166:169], v[236:239], v[6:9]
	v_mfma_f32_16x16x32_bf16 v[6:9], v[162:165], v[232:235], v[6:9]
	v_mfma_f32_16x16x32_bf16 v[2:5], v[170:173], v[232:235], v[2:5]
	v_mfma_f32_16x16x32_bf16 v[2:5], v[178:181], v[236:239], v[2:5]
	v_mfma_f32_16x16x32_bf16 v[10:13], v[178:181], v[228:231], v[10:13]
	v_mfma_f32_16x16x32_bf16 v[10:13], v[170:173], v[206:209], v[10:13]
	v_mfma_f32_16x16x32_bf16 v[26:29], v[170:173], v[198:201], v[26:29]
	v_mfma_f32_16x16x32_bf16 v[26:29], v[178:181], v[202:205], v[26:29]
	v_mfma_f32_16x16x32_bf16 v[42:45], v[178:181], v[194:197], v[42:45]
	v_mfma_f32_16x16x32_bf16 v[42:45], v[170:173], v[190:193], v[42:45]
	s_barrier
	s_setprio 0
.Lz0_3_1_ret:
	s_add_i32 s49, 0, 0x18000
	s_add_i32 s50, 0, 0x1c000
	v_add_u32_e32 v158, s49, v143
	v_add_u32_e32 v175, s50, v143
	ds_read_b128 v[146:149], v158
	ds_read_b128 v[150:153], v158 offset:1024
	ds_read_b128 v[154:157], v158 offset:2048
	ds_read_b128 v[158:161], v158 offset:3072
	ds_read_b128 v[162:165], v175
	ds_read_b128 v[166:169], v175 offset:1024
	ds_read_b128 v[170:173], v175 offset:2048
	ds_read_b128 v[178:181], v175 offset:3072
	s_add_u32 s14, s22, 0x2b0000
	s_addc_u32 s15, s23, 0
	s_mov_b32 m0, s37
	v_lshl_add_u64 v[226:227], s[14:15], 0, v[134:135]
	ds_read_b128 v[190:193], v145 offset:32768
	ds_read_b128 v[194:197], v145 offset:33792
	ds_read_b128 v[198:201], v145 offset:34816
	ds_read_b128 v[202:205], v145 offset:35840
	ds_read_b128 v[206:209], v145 offset:36864
	ds_read_b128 v[228:231], v145 offset:37888
	ds_read_b128 v[232:235], v145 offset:38912
	ds_read_b128 v[236:239], v145 offset:39936
	global_load_lds_dwordx4 v[226:227], off
	s_mov_b32 m0, s38
	v_lshl_add_u64 v[226:227], s[14:15], 0, v[132:133]
	global_load_lds_dwordx4 v[226:227], off
	s_setprio 1
	s_waitcnt vmcnt(8)
	s_waitcnt lgkmcnt(0)
	s_barrier
	v_mfma_f32_16x16x32_bf16 v[126:129], v[146:149], v[190:193], v[126:129]
	v_mfma_f32_16x16x32_bf16 v[126:129], v[150:153], v[194:197], v[126:129]
	v_mfma_f32_16x16x32_bf16 v[118:121], v[150:153], v[202:205], v[118:121]
	v_mfma_f32_16x16x32_bf16 v[118:121], v[146:149], v[198:201], v[118:121]
	v_mfma_f32_16x16x32_bf16 v[102:105], v[146:149], v[206:209], v[102:105]
	v_mfma_f32_16x16x32_bf16 v[102:105], v[150:153], v[228:231], v[102:105]
	v_mfma_f32_16x16x32_bf16 v[86:89], v[150:153], v[236:239], v[86:89]
	v_mfma_f32_16x16x32_bf16 v[86:89], v[146:149], v[232:235], v[86:89]
	v_mfma_f32_16x16x32_bf16 v[78:81], v[154:157], v[232:235], v[78:81]
	v_mfma_f32_16x16x32_bf16 v[78:81], v[158:161], v[236:239], v[78:81]
	v_mfma_f32_16x16x32_bf16 v[94:97], v[158:161], v[228:231], v[94:97]
	v_mfma_f32_16x16x32_bf16 v[94:97], v[154:157], v[206:209], v[94:97]
	v_mfma_f32_16x16x32_bf16 v[110:113], v[154:157], v[198:201], v[110:113]
	v_mfma_f32_16x16x32_bf16 v[110:113], v[158:161], v[202:205], v[110:113]
	v_mfma_f32_16x16x32_bf16 v[122:125], v[158:161], v[194:197], v[122:125]
	v_mfma_f32_16x16x32_bf16 v[122:125], v[154:157], v[190:193], v[122:125]
	v_mfma_f32_16x16x32_bf16 v[114:117], v[162:165], v[190:193], v[114:117]
	v_mfma_f32_16x16x32_bf16 v[114:117], v[166:169], v[194:197], v[114:117]
	v_mfma_f32_16x16x32_bf16 v[98:101], v[166:169], v[202:205], v[98:101]
	v_mfma_f32_16x16x32_bf16 v[98:101], v[162:165], v[198:201], v[98:101]
	v_mfma_f32_16x16x32_bf16 v[82:85], v[162:165], v[206:209], v[82:85]
	v_mfma_f32_16x16x32_bf16 v[82:85], v[166:169], v[228:231], v[82:85]
	v_mfma_f32_16x16x32_bf16 v[70:73], v[166:169], v[236:239], v[70:73]
	v_mfma_f32_16x16x32_bf16 v[70:73], v[162:165], v[232:235], v[70:73]
	v_mfma_f32_16x16x32_bf16 v[66:69], v[170:173], v[232:235], v[66:69]
	v_mfma_f32_16x16x32_bf16 v[66:69], v[178:181], v[236:239], v[66:69]
	v_mfma_f32_16x16x32_bf16 v[74:77], v[178:181], v[228:231], v[74:77]
	v_mfma_f32_16x16x32_bf16 v[74:77], v[170:173], v[206:209], v[74:77]
	v_mfma_f32_16x16x32_bf16 v[90:93], v[170:173], v[198:201], v[90:93]
	v_mfma_f32_16x16x32_bf16 v[90:93], v[178:181], v[202:205], v[90:93]
	v_mfma_f32_16x16x32_bf16 v[106:109], v[178:181], v[194:197], v[106:109]
	v_mfma_f32_16x16x32_bf16 v[106:109], v[170:173], v[190:193], v[106:109]
	s_barrier
	s_setprio 0
	s_add_i32 s14, s49, s26
	s_mov_b32 m0, s14
	v_lshl_add_u64 v[140:141], v[140:141], 0, s[34:35]
	global_load_lds_dwordx4 v[140:141], off
	ds_read_b128 v[190:193], v145 offset:49152
	ds_read_b128 v[194:197], v145 offset:50176
	s_add_i32 m0, s14, 0x2000
	s_add_u32 s14, s18, 0x2b0080
	v_lshl_add_u64 v[140:141], v[186:187], 0, s[34:35]
	s_addc_u32 s15, s19, 0
	s_add_i32 s18, s50, s26
	global_load_lds_dwordx4 v[140:141], off
	ds_read_b128 v[198:201], v145 offset:51200
	ds_read_b128 v[202:205], v145 offset:52224
	s_mov_b32 m0, s18
	v_lshl_add_u64 v[140:141], s[14:15], 0, v[0:1]
	global_load_lds_dwordx4 v[140:141], off
	ds_read_b128 v[206:209], v145 offset:53248
	ds_read_b128 v[228:231], v145 offset:54272
	s_add_i32 m0, s18, 0x2000
	v_lshl_add_u64 v[140:141], s[14:15], 0, v[130:131]
	global_load_lds_dwordx4 v[140:141], off
	ds_read_b128 v[232:235], v145 offset:55296
	ds_read_b128 v[236:239], v145 offset:56320
	s_mov_b32 m0, s39
	v_lshl_add_u64 v[140:141], v[188:189], 0, s[34:35]
	global_load_lds_dwordx4 v[140:141], off
	s_add_i32 s48, s48, 2
	s_add_u32 s46, s46, 0x100
	s_addc_u32 s47, s47, 0
	s_mov_b64 s[14:15], s[16:17]
	s_add_u32 s16, s14, 0x100
	s_addc_u32 s17, s15, 0
	s_cmpk_eq_i32 s48, 0xa8
	s_cselect_b32 s23, s5, s17
	s_cselect_b32 s22, s4, s16
	s_cselect_b32 s19, s9, s47
	s_cselect_b32 s18, s8, s46
	s_mov_b32 m0, s40
	v_lshl_add_u64 v[140:141], v[210:211], 0, s[34:35]
	global_load_lds_dwordx4 v[140:141], off
	s_setprio 1
	s_waitcnt vmcnt(8)
	s_waitcnt lgkmcnt(0)
	s_barrier
	v_mfma_f32_16x16x32_bf16 v[62:65], v[146:149], v[190:193], v[62:65]
	v_mfma_f32_16x16x32_bf16 v[62:65], v[150:153], v[194:197], v[62:65]
	v_mfma_f32_16x16x32_bf16 v[54:57], v[150:153], v[202:205], v[54:57]
	v_mfma_f32_16x16x32_bf16 v[54:57], v[146:149], v[198:201], v[54:57]
	v_mfma_f32_16x16x32_bf16 v[38:41], v[146:149], v[206:209], v[38:41]
	v_mfma_f32_16x16x32_bf16 v[38:41], v[150:153], v[228:231], v[38:41]
	v_mfma_f32_16x16x32_bf16 v[22:25], v[150:153], v[236:239], v[22:25]
	v_mfma_f32_16x16x32_bf16 v[22:25], v[146:149], v[232:235], v[22:25]
	v_mfma_f32_16x16x32_bf16 v[14:17], v[154:157], v[232:235], v[14:17]
	v_mfma_f32_16x16x32_bf16 v[14:17], v[158:161], v[236:239], v[14:17]
	v_mfma_f32_16x16x32_bf16 v[30:33], v[158:161], v[228:231], v[30:33]
	v_mfma_f32_16x16x32_bf16 v[30:33], v[154:157], v[206:209], v[30:33]
	v_mfma_f32_16x16x32_bf16 v[46:49], v[154:157], v[198:201], v[46:49]
	v_mfma_f32_16x16x32_bf16 v[46:49], v[158:161], v[202:205], v[46:49]
	v_mfma_f32_16x16x32_bf16 v[58:61], v[158:161], v[194:197], v[58:61]
	v_mfma_f32_16x16x32_bf16 v[58:61], v[154:157], v[190:193], v[58:61]
	v_mfma_f32_16x16x32_bf16 v[50:53], v[162:165], v[190:193], v[50:53]
	v_mfma_f32_16x16x32_bf16 v[50:53], v[166:169], v[194:197], v[50:53]
	v_mfma_f32_16x16x32_bf16 v[34:37], v[166:169], v[202:205], v[34:37]
	v_mfma_f32_16x16x32_bf16 v[34:37], v[162:165], v[198:201], v[34:37]
	v_mfma_f32_16x16x32_bf16 v[18:21], v[162:165], v[206:209], v[18:21]
	v_mfma_f32_16x16x32_bf16 v[18:21], v[166:169], v[228:231], v[18:21]
	v_mfma_f32_16x16x32_bf16 v[6:9], v[166:169], v[236:239], v[6:9]
	v_mfma_f32_16x16x32_bf16 v[6:9], v[162:165], v[232:235], v[6:9]
	v_mfma_f32_16x16x32_bf16 v[2:5], v[170:173], v[232:235], v[2:5]
	v_mfma_f32_16x16x32_bf16 v[2:5], v[178:181], v[236:239], v[2:5]
	v_mfma_f32_16x16x32_bf16 v[10:13], v[178:181], v[228:231], v[10:13]
	v_mfma_f32_16x16x32_bf16 v[10:13], v[170:173], v[206:209], v[10:13]
	v_mfma_f32_16x16x32_bf16 v[26:29], v[170:173], v[198:201], v[26:29]
	v_mfma_f32_16x16x32_bf16 v[26:29], v[178:181], v[202:205], v[26:29]
	v_mfma_f32_16x16x32_bf16 v[42:45], v[178:181], v[194:197], v[42:45]
	v_mfma_f32_16x16x32_bf16 v[42:45], v[170:173], v[190:193], v[42:45]
	s_barrier
	s_setprio 0
	s_cmpk_gt_u32 s48, 0xa9
	s_cbranch_scc0 .LBB0_805
	s_and_b64 vcc, exec, s[6:7]
	s_cbranch_vccz .LBB0_808
	s_barrier
